# speedup vs baseline: 1.0083x; 1.0035x over previous
; template <int BN, bool SWAP> ...
;     ...
;   auto gl = [&](bf16x8 (&ra)[4], bf16x8 (&rb)[NJ], int kt) {
;     const bool nx = (kt >= nk);
;     const bfu* pa = nx ? (chain ? Apn + (kt - nk) * 64 : Ap + (nk - 1) * 64) : Ap + kt * 64;
;     const bfu* pb = nx ? (chain ? Bpn + (kt - nk) * 64 : Bp + (nk - 1) * 64) : Bp + kt * 64;
;     const size_t sa = (nx && chain) ? (size_t)ldan : (size_t)lda, sb = (nx && chain) ? (size_t)ldbn : (size_t)ldb;
; #pragma unroll
;     for (int q = 0; q < 4; ++q) ra[q] = gld16(pa + (size_t)(32 * q) * sa);
; #pragma unroll
;     for (int q = 0; q < NJ; ++q) rb[q] = gld16(pb + (size_t)(32 * q) * sb);
;   };
;   auto wt = [&](bf16x8 (&ra)[4], bf16x8 (&rb)[NJ]) {
;     if (NJ == 4) asm volatile("s_waitcnt vmcnt(8)" : "+v"(ra[0]), "+v"(ra[1]), "+v"(ra[2]), "+v"(ra[3]), "+v"(rb[0]), "+v"(rb[1]), "+v"(rb[NJ - 2]), "+v"(rb[NJ - 1]) : : "memory");
;     else asm volatile("s_waitcnt vmcnt(6)" : "+v"(ra[0]), "+v"(ra[1]), "+v"(ra[2]), "+v"(ra[3]), "+v"(rb[0]), "+v"(rb[1]) : : "memory");
;   };
;   auto st = [&](const bf16x8 (&ra)[4], const bf16x8 (&rb)[NJ], int buf) {
; #pragma unroll
;     for (int q = 0; q < 4; ++q) *(bf16x8*)(As + (buf * 128 + lrow + 32 * q) * 72 + lch) = ra[q];
; #pragma unroll
;     for (int q = 0; q < NJ; ++q) *(bf16x8*)(Bs + (buf * BN + brow + ((SWAP && NJ == 4) ? (8 * (q & 1) + 64 * (q >> 1)) : 32 * q)) * 72 + lch) = rb[q];
;   };
;   auto comp = [&](int buf, auto&& mid) {
;     const bfu* as = As + buf * 128 * 72 + (wr * 64 + c15) * 72 + g * 8;
;     const bfu* bs = Bs + buf * BN * 72 + (wc * (BN / 2) + c15) * 72 + g * 8;
;     {
;       bf16x8 a0[4], b0[NJ];
; #pragma unroll
;       for (int i = 0; i < 4; ++i) a0[i] = *(const bf16x8*)(as + i * 16 * 72);
; #pragma unroll
;       for (int j = 0; j < NJ; ++j) b0[j] = *(const bf16x8*)(bs + j * 16 * 72);
;       mid();
;       __builtin_amdgcn_s_setprio(1);
; #pragma unroll
;       for (int i = 0; i < 4; ++i)
; #pragma unroll
;         for (int j = 0; j < NJ; ++j) acc[i][j] = SWAP ? MFMA16(b0[j], a0[i], acc[i][j]) : MFMA16(a0[i], b0[j], acc[i][j]);
;       __builtin_amdgcn_s_setprio(0);
;     }
;     {
;       bf16x8 a1[4], b1[NJ];
; #pragma unroll
;       for (int i = 0; i < 4; ++i) a1[i] = *(const bf16x8*)(as + i * 16 * 72 + 32);
; #pragma unroll
;       for (int j = 0; j < NJ; ++j) b1[j] = *(const bf16x8*)(bs + j * 16 * 72 + 32);
;       __builtin_amdgcn_s_setprio(1);
.LBB0_485:
	s_add_i32 s20, s19, 2
	s_sub_i32 s2, s15, 64
	s_cmp_lt_u32 s19, 14
	s_cselect_b64 s[22:23], -1, 0
	s_and_b64 vcc, s[22:23], exec
	s_cselect_b32 s2, s2, 0x3c0
	s_lshl_b64 s[22:23], s[2:3], 1
	v_lshl_add_u64 v[120:121], v[98:99], 0, s[22:23]
	global_load_dwordx4 v[108:111], v[120:121], off
	v_lshl_add_u64 v[112:113], v[120:121], 0, s[76:77]
	global_load_dwordx4 v[112:115], v[112:113], off
	v_lshl_add_u64 v[116:117], v[120:121], 0, s[8:9]
	global_load_dwordx4 v[116:119], v[116:117], off
	v_lshl_add_u64 v[120:121], v[120:121], 0, s[78:79]
	v_lshl_add_u64 v[136:137], v[100:101], 0, s[22:23]
	global_load_dwordx4 v[120:123], v[120:121], off
	global_load_dwordx4 v[124:127], v[136:137], off
	v_lshl_add_u64 v[128:129], v[136:137], 0, s[76:77]
	global_load_dwordx4 v[128:131], v[128:129], off
	v_lshl_add_u64 v[132:133], v[136:137], 0, s[8:9]
	global_load_dwordx4 v[132:135], v[132:133], off
	v_lshl_add_u64 v[136:137], v[136:137], 0, s[78:79]
	global_load_dwordx4 v[136:139], v[136:137], off
	ds_read_b128 v[140:143], v104
	ds_read_b128 v[144:147], v104 offset:2304
	ds_read_b128 v[148:151], v104 offset:4608
	ds_read_b128 v[164:167], v104 offset:6912
	ds_read_b128 v[168:171], v105 offset:36864
	ds_read_b128 v[184:187], v105 offset:39168
	ds_read_b128 v[198:201], v105 offset:41472
	ds_read_b128 v[202:205], v105 offset:43776
	s_waitcnt vmcnt(8)
	ds_write_b128 v102, v[40:43] offset:18432
	ds_write_b128 v102, v[44:47] offset:23040
	ds_write_b128 v102, v[48:51] offset:27648
	ds_write_b128 v102, v[52:55] offset:32256
	ds_write_b128 v103, v[56:59] offset:55296
	ds_write_b128 v103, v[60:63] offset:56448
	ds_write_b128 v103, v[64:67] offset:64512
	ds_write_b128 v106, v[72:75] offset:28800
	s_setprio 1
	s_waitcnt lgkmcnt(11)
	v_mfma_f32_16x16x32_bf16 v[40:43], v[168:171], v[140:143], v[92:95]
	s_waitcnt lgkmcnt(10)
	v_mfma_f32_16x16x32_bf16 v[44:47], v[184:187], v[140:143], v[88:91]
	s_waitcnt lgkmcnt(9)
	v_mfma_f32_16x16x32_bf16 v[48:51], v[198:201], v[140:143], v[84:87]
	s_waitcnt lgkmcnt(8)
	v_mfma_f32_16x16x32_bf16 v[52:55], v[202:205], v[140:143], v[80:83]
	v_mfma_f32_16x16x32_bf16 v[56:59], v[168:171], v[144:147], v[76:79]
	v_mfma_f32_16x16x32_bf16 v[60:63], v[184:187], v[144:147], v[68:71]
	v_mfma_f32_16x16x32_bf16 v[36:39], v[198:201], v[144:147], v[36:39]
	v_mfma_f32_16x16x32_bf16 v[32:35], v[202:205], v[144:147], v[32:35]
	v_mfma_f32_16x16x32_bf16 v[28:31], v[168:171], v[148:151], v[28:31]
	v_mfma_f32_16x16x32_bf16 v[24:27], v[184:187], v[148:151], v[24:27]
	v_mfma_f32_16x16x32_bf16 v[20:23], v[198:201], v[148:151], v[20:23]
	v_mfma_f32_16x16x32_bf16 v[16:19], v[202:205], v[148:151], v[16:19]
	v_mfma_f32_16x16x32_bf16 v[12:15], v[168:171], v[164:167], v[12:15]
	v_mfma_f32_16x16x32_bf16 v[8:11], v[184:187], v[164:167], v[8:11]
	v_mfma_f32_16x16x32_bf16 v[4:7], v[198:201], v[164:167], v[4:7]
	v_mfma_f32_16x16x32_bf16 v[0:3], v[202:205], v[164:167], v[0:3]
	s_setprio 0
	ds_read_b128 v[64:67], v104 offset:64
	ds_read_b128 v[68:71], v104 offset:2368
	ds_read_b128 v[72:75], v104 offset:4672
	ds_read_b128 v[76:79], v104 offset:6976
	ds_read_b128 v[80:83], v105 offset:36928
	ds_read_b128 v[84:87], v105 offset:39232
	ds_read_b128 v[88:91], v105 offset:41536
	ds_read_b128 v[92:95], v105 offset:43840
	s_setprio 1
	s_waitcnt lgkmcnt(1)
	v_mfma_f32_16x16x32_bf16 v[36:39], v[88:91], v[68:71], v[36:39]
	s_waitcnt lgkmcnt(0)
	v_mfma_f32_16x16x32_bf16 v[32:35], v[92:95], v[68:71], v[32:35]
	v_mfma_f32_16x16x32_bf16 v[28:31], v[80:83], v[72:75], v[28:31]
	v_mfma_f32_16x16x32_bf16 v[24:27], v[84:87], v[72:75], v[24:27]
	v_mfma_f32_16x16x32_bf16 v[20:23], v[88:91], v[72:75], v[20:23]
	v_mfma_f32_16x16x32_bf16 v[16:19], v[92:95], v[72:75], v[16:19]
	v_mfma_f32_16x16x32_bf16 v[12:15], v[80:83], v[76:79], v[12:15]
	v_mfma_f32_16x16x32_bf16 v[8:11], v[84:87], v[76:79], v[8:11]
	v_mfma_f32_16x16x32_bf16 v[4:7], v[88:91], v[76:79], v[4:7]
	v_mfma_f32_16x16x32_bf16 v[0:3], v[92:95], v[76:79], v[0:3]
	v_mfma_f32_16x16x32_bf16 v[140:143], v[80:83], v[64:67], v[40:43]
	v_mfma_f32_16x16x32_bf16 v[144:147], v[84:87], v[64:67], v[44:47]
	v_mfma_f32_16x16x32_bf16 v[148:151], v[88:91], v[64:67], v[48:51]
	v_mfma_f32_16x16x32_bf16 v[164:167], v[92:95], v[64:67], v[52:55]
	v_mfma_f32_16x16x32_bf16 v[168:171], v[80:83], v[68:71], v[56:59]
	v_mfma_f32_16x16x32_bf16 v[184:187], v[84:87], v[68:71], v[60:63]
	s_setprio 0
	s_cmp_lt_u32 s19, 13
	s_cselect_b32 s2, s15, 0x3c0
	s_lshl_b64 s[22:23], s[2:3], 1
	v_lshl_add_u64 v[52:53], v[98:99], 0, s[22:23]
	s_barrier
; template <int BN, bool SWAP> ...
;     ...
;   auto st = [&](const bf16x8 (&ra)[4], const bf16x8 (&rb)[NJ], int buf) {
; #pragma unroll
;     for (int q = 0; q < 4; ++q) *(bf16x8*)(As + (buf * 128 + lrow + 32 * q) * 72 + lch) = ra[q];
; #pragma unroll
;     for (int q = 0; q < NJ; ++q) *(bf16x8*)(Bs + (buf * BN + brow + ((SWAP && NJ == 4) ? (8 * (q & 1) + 64 * (q >> 1)) : 32 * q)) * 72 + lch) = rb[q];
;   };
;   auto comp = [&](int buf, auto&& mid) {
;     const bfu* as = As + buf * 128 * 72 + (wr * 64 + c15) * 72 + g * 8;
;     const bfu* bs = Bs + buf * BN * 72 + (wc * (BN / 2) + c15) * 72 + g * 8;
;     {
;       bf16x8 a0[4], b0[NJ];
; #pragma unroll
;       for (int i = 0; i < 4; ++i) a0[i] = *(const bf16x8*)(as + i * 16 * 72);
; #pragma unroll
;       for (int j = 0; j < NJ; ++j) b0[j] = *(const bf16x8*)(bs + j * 16 * 72);
;       mid();
;       __builtin_amdgcn_s_setprio(1);
; #pragma unroll
;       for (int i = 0; i < 4; ++i)
; #pragma unroll
;         for (int j = 0; j < NJ; ++j) acc[i][j] = SWAP ? MFMA16(b0[j], a0[i], acc[i][j]) : MFMA16(a0[i], b0[j], acc[i][j]);
;       __builtin_amdgcn_s_setprio(0);
;     }
;     {
;       bf16x8 a1[4], b1[NJ];
; #pragma unroll
;       for (int i = 0; i < 4; ++i) a1[i] = *(const bf16x8*)(as + i * 16 * 72 + 32);
; #pragma unroll
;       for (int j = 0; j < NJ; ++j) b1[j] = *(const bf16x8*)(bs + j * 16 * 72 + 32);
;       __builtin_amdgcn_s_setprio(1);
; #pragma unroll
;       for (int i = 0; i < 4; ++i)
; #pragma unroll
;         for (int j = 0; j < NJ; ++j) acc[i][j] = SWAP ? MFMA16(b1[j], a1[i], acc[i][j]) : MFMA16(a1[i], b1[j], acc[i][j]);
;       __builtin_amdgcn_s_setprio(0);
;     }
; template <int G>
; __device__ __forceinline__ void p5(const Params& P, const Ptrs<G>& w, int pass, int layer, bfu* sm, const XcdInfo& xi) {
;     ...
;     const size_t eb = (size_t)(m0 + wr * 64 + c15) * 1024 + n0 + wc * 64 + 16 * g;
; #pragma unroll
;     for (int i = 0; i < 4; ++i) {
;       const size_t e = eb + (size_t)(16 * i) * 1024;
;       unsigned pk[8];
; #pragma unroll
;       for (int j = 0; j < 4; ++j) {
;         const float4 x0 = *(const float4*)(xres + e + 4 * j);
;         float4 v;
;         v.x = ALPHA_DN * x0.x + C[i][j][0]; v.y = ALPHA_DN * x0.y + C[i][j][1]; v.z = ALPHA_DN * x0.z + C[i][j][2]; v.w = ALPHA_DN * x0.w + C[i][j][3];
;         *(float4*)(w.r() + e + 4 * j) = v;
	global_load_dwordx4 v[40:43], v[52:53], off
	v_lshl_add_u64 v[44:45], v[52:53], 0, s[76:77]
	global_load_dwordx4 v[44:47], v[44:45], off
	v_lshl_add_u64 v[48:49], v[52:53], 0, s[8:9]
	global_load_dwordx4 v[48:51], v[48:49], off
	v_lshl_add_u64 v[52:53], v[52:53], 0, s[78:79]
	v_lshl_add_u64 v[68:69], v[100:101], 0, s[22:23]
	global_load_dwordx4 v[52:55], v[52:53], off
	global_load_dwordx4 v[56:59], v[68:69], off
	v_lshl_add_u64 v[60:61], v[68:69], 0, s[76:77]
	global_load_dwordx4 v[60:63], v[60:61], off
	v_lshl_add_u64 v[64:65], v[68:69], 0, s[8:9]
	global_load_dwordx4 v[64:67], v[64:65], off
	v_lshl_add_u64 v[68:69], v[68:69], 0, s[78:79]
	global_load_dwordx4 v[72:75], v[68:69], off
	ds_read_b128 v[68:71], v104 offset:18432
	ds_read_b128 v[76:79], v104 offset:20736
	ds_read_b128 v[80:83], v104 offset:23040
	ds_read_b128 v[84:87], v104 offset:25344
	ds_read_b128 v[88:91], v105 offset:55296
	ds_read_b128 v[92:95], v105 offset:57600
	ds_read_b128 v[198:201], v105 offset:59904
	ds_read_b128 v[202:205], v105 offset:62208
	s_waitcnt vmcnt(8)
	ds_write_b128 v102, v[108:111]
	ds_write_b128 v102, v[112:115] offset:4608
	ds_write_b128 v102, v[116:119] offset:9216
	ds_write_b128 v102, v[120:123] offset:13824
	ds_write_b128 v103, v[124:127] offset:36864
	ds_write_b128 v103, v[128:131] offset:38016
	ds_write_b128 v103, v[132:135] offset:46080
	ds_write_b128 v103, v[136:139] offset:47232
	s_setprio 1
	s_waitcnt lgkmcnt(11)
	v_mfma_f32_16x16x32_bf16 v[108:111], v[88:91], v[68:71], v[140:143]
	s_waitcnt lgkmcnt(10)
	v_mfma_f32_16x16x32_bf16 v[112:115], v[92:95], v[68:71], v[144:147]
	s_waitcnt lgkmcnt(9)
	v_mfma_f32_16x16x32_bf16 v[116:119], v[198:201], v[68:71], v[148:151]
	s_waitcnt lgkmcnt(8)
	v_mfma_f32_16x16x32_bf16 v[68:71], v[202:205], v[68:71], v[164:167]
	v_mfma_f32_16x16x32_bf16 v[36:39], v[198:201], v[76:79], v[36:39]
	v_mfma_f32_16x16x32_bf16 v[32:35], v[202:205], v[76:79], v[32:35]
	v_mfma_f32_16x16x32_bf16 v[28:31], v[88:91], v[80:83], v[28:31]
	v_mfma_f32_16x16x32_bf16 v[24:27], v[92:95], v[80:83], v[24:27]
	v_mfma_f32_16x16x32_bf16 v[20:23], v[198:201], v[80:83], v[20:23]
	v_mfma_f32_16x16x32_bf16 v[16:19], v[202:205], v[80:83], v[16:19]
	v_mfma_f32_16x16x32_bf16 v[12:15], v[88:91], v[84:87], v[12:15]
	v_mfma_f32_16x16x32_bf16 v[8:11], v[92:95], v[84:87], v[8:11]
	v_mfma_f32_16x16x32_bf16 v[4:7], v[198:201], v[84:87], v[4:7]
	v_mfma_f32_16x16x32_bf16 v[0:3], v[202:205], v[84:87], v[0:3]
	v_mfma_f32_16x16x32_bf16 v[120:123], v[88:91], v[76:79], v[168:171]
	v_mfma_f32_16x16x32_bf16 v[124:127], v[92:95], v[76:79], v[184:187]
	s_setprio 0
	ds_read_b128 v[76:79], v104 offset:18496
	ds_read_b128 v[128:131], v104 offset:20800
	ds_read_b128 v[132:135], v104 offset:23104
	ds_read_b128 v[136:139], v104 offset:25408
	ds_read_b128 v[140:143], v105 offset:55360
	ds_read_b128 v[144:147], v105 offset:57664
	ds_read_b128 v[148:151], v105 offset:59968
	ds_read_b128 v[164:167], v105 offset:62272
	s_setprio 1
	s_waitcnt lgkmcnt(3)
	v_mfma_f32_16x16x32_bf16 v[92:95], v[140:143], v[76:79], v[108:111]
	s_waitcnt lgkmcnt(2)
	v_mfma_f32_16x16x32_bf16 v[88:91], v[144:147], v[76:79], v[112:115]
	s_waitcnt lgkmcnt(1)
	v_mfma_f32_16x16x32_bf16 v[84:87], v[148:151], v[76:79], v[116:119]
	s_waitcnt lgkmcnt(0)
	v_mfma_f32_16x16x32_bf16 v[80:83], v[164:167], v[76:79], v[68:71]
	v_mfma_f32_16x16x32_bf16 v[76:79], v[140:143], v[128:131], v[120:123]
	v_mfma_f32_16x16x32_bf16 v[68:71], v[144:147], v[128:131], v[124:127]
	v_mfma_f32_16x16x32_bf16 v[36:39], v[148:151], v[128:131], v[36:39]
	v_mfma_f32_16x16x32_bf16 v[32:35], v[164:167], v[128:131], v[32:35]
	v_mfma_f32_16x16x32_bf16 v[28:31], v[140:143], v[132:135], v[28:31]
	v_mfma_f32_16x16x32_bf16 v[24:27], v[144:147], v[132:135], v[24:27]
	v_mfma_f32_16x16x32_bf16 v[20:23], v[148:151], v[132:135], v[20:23]
	v_mfma_f32_16x16x32_bf16 v[16:19], v[164:167], v[132:135], v[16:19]
	v_mfma_f32_16x16x32_bf16 v[12:15], v[140:143], v[136:139], v[12:15]
	v_mfma_f32_16x16x32_bf16 v[8:11], v[144:147], v[136:139], v[8:11]
	v_mfma_f32_16x16x32_bf16 v[4:7], v[148:151], v[136:139], v[4:7]
	v_mfma_f32_16x16x32_bf16 v[0:3], v[164:167], v[136:139], v[0:3]
	s_setprio 0
	s_addk_i32 s15, 0x80
	s_mov_b32 s19, s20
	s_barrier
	s_cbranch_vccnz .LBB0_485
	s_waitcnt vmcnt(0)
	s_mov_b32 s20, 0x3fb504f3
	v_add_u32_e32 v40, s14, v97
	v_ashrrev_i32_e32 v41, 31, v40
	v_lshlrev_b64 v[40:41], 10, v[40:41]
	v_mov_b32_e32 v43, s13
	v_or_b32_e32 v42, s12, v96
	v_lshl_add_u64 v[40:41], v[40:41], 0, v[42:43]
	v_lshlrev_b64 v[44:45], 2, v[40:41]
	v_lshl_add_u64 v[46:47], s[0:1], 0, v[44:45]
	global_load_dwordx4 v[48:51], v[46:47], off
	global_load_dwordx4 v[52:55], v[46:47], off offset:16
	global_load_dwordx4 v[56:59], v[46:47], off offset:32
	global_load_dwordx4 v[60:63], v[46:47], off offset:48
	v_lshl_add_u64 v[42:43], s[66:67], 0, v[44:45]
	v_readlane_b32 s12, v253, 38
	v_readlane_b32 s14, v253, 40
	v_readlane_b32 s15, v253, 41
	s_mov_b32 s2, 0x14121000
	v_readlane_b32 s13, v253, 39
	v_lshl_add_u64 v[44:45], s[14:15], 0, v[44:45]
	v_add_co_u32_e32 v72, vcc, s2, v44
	v_readlane_b32 s12, v252, 38
	s_nop 0
	v_addc_co_u32_e32 v73, vcc, 0, v45, vcc
	v_readlane_b32 s13, v252, 39
	s_waitcnt vmcnt(3)
	v_pk_fma_f32 v[48:49], v[48:49], s[20:21], v[92:93] op_sel_hi:[1,0,1]
	v_pk_fma_f32 v[50:51], v[50:51], s[20:21], v[94:95] op_sel_hi:[1,0,1]
	global_store_dwordx4 v[42:43], v[48:51], off
	v_lshl_add_u64 v[40:41], v[40:41], 1, s[12:13]
	v_cvt_pk_bf16_f32 v65, v50, v51
	v_cvt_pk_bf16_f32 v64, v48, v49
	s_waitcnt vmcnt(3)
	v_pk_fma_f32 v[52:53], v[52:53], s[20:21], v[88:89] op_sel_hi:[1,0,1]
	v_pk_fma_f32 v[54:55], v[54:55], s[20:21], v[90:91] op_sel_hi:[1,0,1]
	global_store_dwordx4 v[72:73], v[52:55], off offset:2064
	v_cvt_pk_bf16_f32 v67, v54, v55
	v_cvt_pk_bf16_f32 v66, v52, v53
	s_waitcnt vmcnt(3)
;   __device__ __forceinline__ bfu* rb() const { return (bfu*)(b + L::o_rb); }
;   __device__ __forceinline__ float* r() const { return (float*)(b + L::o_r); }
; template <int G>
; __device__ __forceinline__ void p5(const Params& P, const Ptrs<G>& w, int pass, int layer, bfu* sm, const XcdInfo& xi) {
;     ...
;     for (int i = 0; i < 4; ++i) {
;       const size_t e = eb + (size_t)(16 * i) * 1024;
;       unsigned pk[8];
; #pragma unroll
;       for (int j = 0; j < 4; ++j) {
;         const float4 x0 = *(const float4*)(xres + e + 4 * j);
;         float4 v;
;         v.x = ALPHA_DN * x0.x + C[i][j][0]; v.y = ALPHA_DN * x0.y + C[i][j][1]; v.z = ALPHA_DN * x0.z + C[i][j][2]; v.w = ALPHA_DN * x0.w + C[i][j][3];
;         *(float4*)(w.r() + e + 4 * j) = v;
;         pk[2 * j] = pack2(v.x, v.y); pk[2 * j + 1] = pack2(v.z, v.w);
;       }
;       *(uint4*)(w.rb() + e) = make_uint4(pk[0], pk[1], pk[2], pk[3]);
;       *(uint4*)(w.rb() + e + 8) = make_uint4(pk[4], pk[5], pk[6], pk[7]);
;       __builtin_amdgcn_sched_barrier(0);
;     }
;   }
	v_pk_fma_f32 v[56:57], v[56:57], s[20:21], v[84:85] op_sel_hi:[1,0,1]
	v_pk_fma_f32 v[58:59], v[58:59], s[20:21], v[86:87] op_sel_hi:[1,0,1]
	global_store_dwordx4 v[72:73], v[56:59], off offset:2080
	v_cvt_pk_bf16_f32 v49, v58, v59
	v_cvt_pk_bf16_f32 v48, v56, v57
	s_waitcnt vmcnt(3)
	v_pk_fma_f32 v[52:53], v[60:61], s[20:21], v[80:81] op_sel_hi:[1,0,1]
	v_pk_fma_f32 v[54:55], v[62:63], s[20:21], v[82:83] op_sel_hi:[1,0,1]
	v_cvt_pk_bf16_f32 v50, v52, v53
	v_cvt_pk_bf16_f32 v51, v54, v55
	global_store_dwordx4 v[72:73], v[52:55], off offset:2096
	global_store_dwordx4 v[40:41], v[64:67], off
	global_store_dwordx4 v[40:41], v[48:51], off offset:16
	s_mov_b32 s12, 0x10000
	s_nop 0
	v_add_co_u32_e32 v48, vcc, s12, v46
	v_lshl_add_u64 v[60:61], v[46:47], 0, s[76:77]
	s_nop 0
	v_addc_co_u32_e32 v49, vcc, 0, v47, vcc
	global_load_dwordx4 v[48:51], v[48:49], off
	global_load_dwordx4 v[80:83], v[60:61], off offset:16
	global_load_dwordx4 v[84:87], v[60:61], off offset:32
	global_load_dwordx4 v[88:91], v[60:61], off offset:48
	v_add_co_u32_e32 v52, vcc, s12, v42
	s_mov_b32 s2, 0x14131000
	s_nop 0
	v_addc_co_u32_e32 v53, vcc, 0, v43, vcc
	v_add_co_u32_e32 v62, vcc, s2, v44
	s_waitcnt vmcnt(3)
	v_pk_fma_f32 v[48:49], v[48:49], s[20:21], v[76:77] op_sel_hi:[1,0,1]
	v_pk_fma_f32 v[50:51], v[50:51], s[20:21], v[78:79] op_sel_hi:[1,0,1]
	global_store_dwordx4 v[52:53], v[48:51], off
	v_addc_co_u32_e32 v63, vcc, 0, v45, vcc
	s_waitcnt vmcnt(3)
	v_pk_fma_f32 v[52:53], v[80:81], s[20:21], v[68:69] op_sel_hi:[1,0,1]
	v_pk_fma_f32 v[54:55], v[82:83], s[20:21], v[70:71] op_sel_hi:[1,0,1]
	global_store_dwordx4 v[62:63], v[52:55], off offset:2064
	s_waitcnt vmcnt(3)
	v_pk_fma_f32 v[36:37], v[84:85], s[20:21], v[36:37] op_sel_hi:[1,0,1]
	v_pk_fma_f32 v[38:39], v[86:87], s[20:21], v[38:39] op_sel_hi:[1,0,1]
	global_store_dwordx4 v[62:63], v[36:39], off offset:2080
	v_lshl_add_u64 v[60:61], v[40:41], 0, s[6:7]
	s_waitcnt vmcnt(3)
	v_pk_fma_f32 v[32:33], v[88:89], s[20:21], v[32:33] op_sel_hi:[1,0,1]
	v_cvt_pk_bf16_f32 v56, v48, v49
	v_add_co_u32_e32 v48, vcc, s88, v40
	v_pk_fma_f32 v[34:35], v[90:91], s[20:21], v[34:35] op_sel_hi:[1,0,1]
	v_cvt_pk_bf16_f32 v57, v50, v51
	v_cvt_pk_bf16_f32 v59, v54, v55
	v_cvt_pk_bf16_f32 v58, v52, v53
	v_addc_co_u32_e32 v49, vcc, 0, v41, vcc
	global_store_dwordx4 v[62:63], v[32:35], off offset:2096
	global_store_dwordx4 v[48:49], v[56:59], off
	v_cvt_pk_bf16_f32 v49, v38, v39
	v_cvt_pk_bf16_f32 v51, v34, v35
	v_cvt_pk_bf16_f32 v48, v36, v37
	v_cvt_pk_bf16_f32 v50, v32, v33
	global_store_dwordx4 v[60:61], v[48:51], off offset:16
	s_mov_b32 s2, 0x20000
	v_add_co_u32_e32 v32, vcc, s2, v46
	v_lshl_add_u64 v[36:37], v[46:47], 0, s[8:9]
	s_nop 0
	v_addc_co_u32_e32 v33, vcc, 0, v47, vcc
	global_load_dwordx4 v[32:35], v[32:33], off
	global_load_dwordx4 v[80:83], v[36:37], off offset:16
	global_load_dwordx4 v[84:87], v[36:37], off offset:32
	global_load_dwordx4 v[88:91], v[36:37], off offset:48
	s_mov_b32 s7, 0x20000
	s_waitcnt vmcnt(3)
	v_pk_fma_f32 v[28:29], v[32:33], s[20:21], v[28:29] op_sel_hi:[1,0,1]
	v_add_co_u32_e32 v32, vcc, s2, v42
	v_pk_fma_f32 v[30:31], v[34:35], s[20:21], v[30:31] op_sel_hi:[1,0,1]
	s_nop 0
	v_addc_co_u32_e32 v33, vcc, 0, v43, vcc
	global_store_dwordx4 v[32:33], v[28:31], off
	s_mov_b32 s2, 0x14141000
	v_add_co_u32_e32 v38, vcc, s2, v44
	v_cvt_pk_bf16_f32 v31, v30, v31
	s_nop 0
	v_addc_co_u32_e32 v39, vcc, 0, v45, vcc
	v_cvt_pk_bf16_f32 v30, v28, v29
	s_waitcnt vmcnt(3)
	v_pk_fma_f32 v[24:25], v[80:81], s[20:21], v[24:25] op_sel_hi:[1,0,1]
	v_pk_fma_f32 v[26:27], v[82:83], s[20:21], v[26:27] op_sel_hi:[1,0,1]
	global_store_dwordx4 v[38:39], v[24:27], off offset:2064
	s_waitcnt vmcnt(3)
	v_pk_fma_f32 v[20:21], v[84:85], s[20:21], v[20:21] op_sel_hi:[1,0,1]
	v_pk_fma_f32 v[22:23], v[86:87], s[20:21], v[22:23] op_sel_hi:[1,0,1]
	global_store_dwordx4 v[38:39], v[20:23], off offset:2080
	s_waitcnt vmcnt(3)
	v_pk_fma_f32 v[16:17], v[88:89], s[20:21], v[16:17] op_sel_hi:[1,0,1]
	v_cvt_pk_bf16_f32 v32, v24, v25
	v_add_co_u32_e32 v24, vcc, s12, v40
	v_pk_fma_f32 v[18:19], v[90:91], s[20:21], v[18:19] op_sel_hi:[1,0,1]
	v_cvt_pk_bf16_f32 v33, v26, v27
	v_addc_co_u32_e32 v25, vcc, 0, v41, vcc
	global_store_dwordx4 v[38:39], v[16:19], off offset:2096
	v_lshl_add_u64 v[34:35], v[40:41], 0, s[76:77]
	global_store_dwordx4 v[24:25], v[30:33], off
	v_cvt_pk_bf16_f32 v23, v22, v23
	v_cvt_pk_bf16_f32 v25, v18, v19
	v_cvt_pk_bf16_f32 v22, v20, v21
	v_cvt_pk_bf16_f32 v24, v16, v17
	global_store_dwordx4 v[34:35], v[22:25], off offset:16
	v_add_co_u32_e32 v16, vcc, s75, v46
	v_lshl_add_u64 v[20:21], v[46:47], 0, s[78:79]
	s_nop 0
	v_addc_co_u32_e32 v17, vcc, 0, v47, vcc
	global_load_dwordx4 v[16:19], v[16:17], off
	global_load_dwordx4 v[80:83], v[20:21], off offset:16
	global_load_dwordx4 v[84:87], v[20:21], off offset:32
	global_load_dwordx4 v[88:91], v[20:21], off offset:48
	v_add_co_u32_e32 v22, vcc, s75, v42
	s_mov_b32 s2, 0x14151000
	s_nop 0
	v_addc_co_u32_e32 v23, vcc, 0, v43, vcc
	v_add_co_u32_e32 v24, vcc, s2, v44
	s_mov_b64 s[12:13], 0x18000
	s_nop 0
	v_addc_co_u32_e32 v25, vcc, 0, v45, vcc
	s_mov_b32 s2, 0x18000
	v_lshl_add_u64 v[26:27], v[40:41], 0, s[12:13]
	v_add_co_u32_e32 v28, vcc, s2, v40
	s_waitcnt vmcnt(3)
	v_pk_fma_f32 v[12:13], v[16:17], s[20:21], v[12:13] op_sel_hi:[1,0,1]
	v_pk_fma_f32 v[14:15], v[18:19], s[20:21], v[14:15] op_sel_hi:[1,0,1]
	global_store_dwordx4 v[22:23], v[12:15], off
	v_addc_co_u32_e32 v29, vcc, 0, v41, vcc
	s_waitcnt vmcnt(3)
	v_pk_fma_f32 v[8:9], v[80:81], s[20:21], v[8:9] op_sel_hi:[1,0,1]
	v_pk_fma_f32 v[10:11], v[82:83], s[20:21], v[10:11] op_sel_hi:[1,0,1]
	global_store_dwordx4 v[24:25], v[8:11], off offset:2064
	v_cvt_pk_bf16_f32 v22, v8, v9
	v_cvt_pk_bf16_f32 v23, v10, v11
	s_waitcnt vmcnt(3)
	v_pk_fma_f32 v[4:5], v[84:85], s[20:21], v[4:5] op_sel_hi:[1,0,1]
	v_pk_fma_f32 v[6:7], v[86:87], s[20:21], v[6:7] op_sel_hi:[1,0,1]
	global_store_dwordx4 v[24:25], v[4:7], off offset:2080
	v_cvt_pk_bf16_f32 v21, v14, v15
	v_cvt_pk_bf16_f32 v7, v6, v7
	v_cvt_pk_bf16_f32 v6, v4, v5
	v_cvt_pk_bf16_f32 v20, v12, v13
	s_waitcnt vmcnt(3)
	v_pk_fma_f32 v[0:1], v[88:89], s[20:21], v[0:1] op_sel_hi:[1,0,1]
	v_pk_fma_f32 v[2:3], v[90:91], s[20:21], v[2:3] op_sel_hi:[1,0,1]
	v_cvt_pk_bf16_f32 v8, v0, v1
	v_cvt_pk_bf16_f32 v9, v2, v3
	global_store_dwordx4 v[24:25], v[0:3], off offset:2096
	global_store_dwordx4 v[28:29], v[20:23], off
	global_store_dwordx4 v[26:27], v[6:9], off offset:16
	v_readlane_b32 s2, v254, 27
	s_add_i32 s18, s18, s2
	v_readlane_b32 s2, v254, 34
	s_cmp_lt_i32 s18, s2
	s_cbranch_scc1 .LBB0_480
	v_readlane_b32 s6, v254, 49
